# on top of v36: nt hint on the read-once dwordx4 loads of the conversion/norm phases 0, 8 and 16 (f32 weights, x, Y)
# speedup vs baseline: 1.0015x; 1.0015x over previous
.LBB0_24:
	v_lshlrev_b32_e32 v1, 2, v14
	v_and_b32_e32 v1, 60, v1
	v_add_u32_e32 v2, s31, v1
	v_lshlrev_b32_e32 v3, 1, v2
	v_ashrrev_i32_e32 v4, 3, v2
	v_and_b32_e32 v3, 0x700, v3
	v_and_b32_e32 v4, 0xffffff80, v4
	v_add_u32_e32 v3, v3, v4
	s_movk_i32 s11, 0x7f
	v_ashrrev_i32_e32 v16, 4, v14
	v_and_or_b32 v3, v2, s11, v3
	v_cndmask_b32_e64 v6, v2, v3, s[20:21]
	v_mov_b32_e32 v7, 0
	v_add_u32_e32 v8, s10, v16
	v_cmp_lt_i32_e32 vcc, -1, v6
	v_mov_b32_e32 v2, v7
	v_mov_b32_e32 v3, v7
	v_mov_b32_e32 v4, v7
	v_mov_b32_e32 v5, v7
	v_ashrrev_i32_e32 v9, 31, v8
	s_and_saveexec_b64 s[14:15], vcc
	s_cbranch_execz .LBB0_26
	v_mul_lo_u32 v4, s18, v9
	v_mul_lo_u32 v5, s19, v8
	v_mad_u64_u32 v[2:3], s[20:21], s18, v8, 0
	v_add3_u32 v3, v3, v4, v5
	v_lshl_add_u64 v[2:3], v[2:3], 2, s[12:13]
	v_lshl_add_u64 v[2:3], v[6:7], 2, v[2:3]
	global_load_dwordx4 v[2:5], v[2:3], off nt

.LBB0_28:
	v_mov_b32_e32 v10, 0
	v_add_u32_e32 v18, 32, v16
	v_mov_b32_e32 v11, v10
	v_mov_b32_e32 v12, v10
	v_mov_b32_e32 v13, v10
	s_and_saveexec_b64 s[20:21], vcc
	s_cbranch_execz .LBB0_30
	v_add_u32_e32 v8, s10, v18
	v_ashrrev_i32_e32 v9, 31, v8
	v_mul_lo_u32 v10, s18, v9
	v_mul_lo_u32 v11, s19, v8
	v_mad_u64_u32 v[8:9], s[18:19], s18, v8, 0
	v_add3_u32 v9, v9, v10, v11
	v_lshl_add_u64 v[8:9], v[8:9], 2, s[12:13]
	v_lshl_add_u64 v[6:7], v[6:7], 2, v[8:9]
	global_load_dwordx4 v[10:13], v[6:7], off nt

.LBB0_48:
	v_add_u32_e32 v2, s50, v1
	v_lshlrev_b32_e32 v3, 1, v2
	v_ashrrev_i32_e32 v4, 3, v2
	v_and_b32_e32 v3, 0x700, v3
	v_and_b32_e32 v4, 0xffffff80, v4
	v_add_u32_e32 v3, v3, v4
	v_and_or_b32 v3, v2, s48, v3
	v_cndmask_b32_e64 v10, v2, v3, s[26:27]
	v_add_u32_e32 v6, s18, v16
	v_cmp_lt_i32_e32 vcc, -1, v10
	v_mov_b32_e32 v2, v11
	v_mov_b32_e32 v3, v11
	v_mov_b32_e32 v4, v11
	v_mov_b32_e32 v5, v11
	v_ashrrev_i32_e32 v7, 31, v6
	s_and_saveexec_b64 s[20:21], vcc
	s_cbranch_execz .LBB0_50
	v_mul_lo_u32 v4, s24, v7
	v_mul_lo_u32 v5, s25, v6
	v_mad_u64_u32 v[2:3], s[26:27], s24, v6, 0
	v_add3_u32 v3, v3, v4, v5
	v_lshl_add_u64 v[2:3], v[2:3], 2, s[16:17]
	v_lshl_add_u64 v[2:3], v[10:11], 2, v[2:3]
	global_load_dwordx4 v[2:5], v[2:3], off nt

.LBB0_52:
	v_mov_b32_e32 v6, v11
	v_mov_b32_e32 v7, v11
	v_mov_b32_e32 v8, v11
	v_mov_b32_e32 v9, v11
	s_and_saveexec_b64 s[26:27], vcc
	s_cbranch_execz .LBB0_54
	v_add_u32_e32 v6, s18, v18
	v_ashrrev_i32_e32 v7, 31, v6
	v_mul_lo_u32 v8, s24, v7
	v_mul_lo_u32 v9, s25, v6
	v_mad_u64_u32 v[6:7], s[24:25], s24, v6, 0
	v_add3_u32 v7, v7, v8, v9
	v_lshl_add_u64 v[6:7], v[6:7], 2, s[16:17]
	v_lshl_add_u64 v[6:7], v[10:11], 2, v[6:7]
	global_load_dwordx4 v[6:9], v[6:7], off nt

.LBB0_58:
	s_mov_b64 s[16:17], s[76:77]
	v_cmp_lt_i32_e32 vcc, v7, v6
	s_load_dwordx2 s[20:21], s[16:17], 0x0
	s_mov_b64 s[18:19], s[76:77]
	v_cndmask_b32_e32 v21, v1, v7, vcc
	v_cmp_lt_i32_e32 vcc, v8, v6
	s_waitcnt lgkmcnt(0)
	v_lshl_add_u64 v[58:59], s[20:21], 0, v[4:5]
	s_load_dwordx2 s[16:17], s[18:19], 0x10
	v_cndmask_b32_e32 v22, v1, v8, vcc
	v_cmp_lt_i32_e32 vcc, v9, v6
	v_lshlrev_b32_e32 v74, 2, v22
	v_lshlrev_b32_e32 v21, 2, v21
	v_cndmask_b32_e32 v23, v1, v9, vcc
	v_cmp_lt_i32_e32 vcc, v10, v6
	v_lshlrev_b32_e32 v75, 2, v23
	s_add_i32 s8, s8, s10
	v_cndmask_b32_e32 v24, v1, v10, vcc
	v_cmp_lt_i32_e32 vcc, v11, v6
	v_lshlrev_b32_e32 v76, 2, v24
	s_cmpk_lt_i32 s8, 0x4000
	v_cndmask_b32_e32 v25, v1, v11, vcc
	v_cmp_lt_i32_e32 vcc, v12, v6
	v_lshlrev_b32_e32 v77, 2, v25
	v_lshl_add_u64 v[4:5], v[4:5], 0, s[14:15]
	v_cndmask_b32_e32 v26, v1, v12, vcc
	v_lshlrev_b32_e32 v78, 2, v26
	global_load_dwordx4 v[22:25], v[58:59], off offset:-3072 nt
	global_load_dwordx4 v[26:29], v[58:59], off offset:-2048 nt
	global_load_dwordx4 v[30:33], v[58:59], off offset:-4096 nt
	v_add_co_u32_e32 v60, vcc, 0xfffff000, v58
	global_load_dwordx4 v[34:37], v[58:59], off offset:-1024 nt
	s_nop 0
	v_addc_co_u32_e32 v61, vcc, -1, v59, vcc
	global_load_dwordx4 v[38:41], v[60:61], off offset:-2048 nt
	global_load_dwordx4 v[42:45], v[60:61], off offset:-1024 nt
	global_load_dwordx4 v[46:49], v[60:61], off offset:-3072 nt
	global_load_dwordx4 v[50:53], v[58:59], off nt
	s_waitcnt lgkmcnt(0)
	global_load_dwordx4 v[54:57], v16, s[16:17]
	s_waitcnt vmcnt(8)
	v_mov_b32_e32 v60, v23
	s_waitcnt vmcnt(7)
	v_mov_b32_e32 v61, v27
	v_mov_b32_e32 v58, v22
	v_mov_b32_e32 v59, v26
	v_pk_mul_f32 v[60:61], v[60:61], v[60:61]
	v_mov_b32_e32 v62, v24
	s_waitcnt vmcnt(2)
	v_mul_f32_e32 v80, v47, v47
	v_pk_fma_f32 v[58:59], v[58:59], v[58:59], v[60:61]
	v_mul_f32_e32 v60, v39, v39
	v_mov_b32_e32 v63, v28
	v_mov_b32_e32 v68, v35
	s_waitcnt vmcnt(1)
	v_mov_b32_e32 v69, v51
	v_mul_f32_e32 v61, v43, v43
	v_fmac_f32_e32 v80, v46, v46
	v_fmac_f32_e32 v60, v38, v38
	v_mov_b32_e32 v66, v34
	v_mul_f32_e32 v79, v31, v31
	s_waitcnt vmcnt(0)
	v_pk_mul_f32 v[54:55], v[46:47], v[54:55]
	v_mov_b32_e32 v67, v50
	v_pk_fma_f32 v[46:47], v[62:63], v[62:63], v[58:59]
	v_pk_mul_f32 v[58:59], v[68:69], v[68:69]
	v_fmac_f32_e32 v61, v42, v42
	v_fmac_f32_e32 v80, v48, v48
	v_fmac_f32_e32 v60, v40, v40
	v_mov_b32_e32 v70, v36
	v_fmac_f32_e32 v79, v30, v30
	v_mov_b32_e32 v71, v52
	v_pk_fma_f32 v[58:59], v[66:67], v[66:67], v[58:59]
	v_fmac_f32_e32 v61, v44, v44
	v_fmac_f32_e32 v80, v49, v49
	v_fmac_f32_e32 v60, v41, v41
	v_pk_mul_f32 v[56:57], v[48:49], v[56:57]
	v_fmac_f32_e32 v79, v32, v32
	v_pk_fma_f32 v[48:49], v[70:71], v[70:71], v[58:59]
	v_fmac_f32_e32 v61, v45, v45
	v_add_f32_e32 v58, v80, v60
	v_mov_b32_e32 v64, v25
	v_mov_b32_e32 v65, v29
	v_fmac_f32_e32 v79, v33, v33
	v_add_f32_e32 v58, v58, v61
	v_pk_fma_f32 v[46:47], v[64:65], v[64:65], v[46:47]
	v_add_f32_e32 v58, v58, v79
	v_mov_b32_e32 v72, v37
	v_mov_b32_e32 v73, v53
	v_add_f32_e32 v46, v58, v46
	v_pk_fma_f32 v[48:49], v[72:73], v[72:73], v[48:49]
	v_add_f32_e32 v46, v46, v47
	v_add_f32_e32 v46, v46, v48
	v_add_f32_e32 v46, v46, v49
	ds_bpermute_b32 v21, v21, v46
	s_waitcnt lgkmcnt(0)
	v_add_f32_e32 v21, v46, v21
	ds_bpermute_b32 v46, v74, v21
	s_waitcnt lgkmcnt(0)
	v_add_f32_e32 v21, v21, v46
	ds_bpermute_b32 v46, v75, v21
	s_waitcnt lgkmcnt(0)
	v_add_f32_e32 v21, v21, v46
	ds_bpermute_b32 v46, v76, v21
	s_waitcnt lgkmcnt(0)
	v_add_f32_e32 v21, v21, v46
	ds_bpermute_b32 v46, v77, v21
	s_waitcnt lgkmcnt(0)
	v_add_f32_e32 v21, v21, v46
	ds_bpermute_b32 v46, v78, v21
	s_waitcnt lgkmcnt(0)
	v_add_f32_e32 v21, v21, v46
	v_fmamk_f32 v21, v21, 0x3a000000, v13
	v_mul_f32_e32 v46, 0x4b800000, v21
	v_cmp_gt_f32_e32 vcc, s9, v21
	s_nop 1
	v_cndmask_b32_e32 v21, v21, v46, vcc
	v_rsq_f32_e32 v21, v21
	s_nop 0
	v_mul_f32_e32 v46, 0x45800000, v21
	v_cndmask_b32_e32 v58, v21, v46, vcc
	v_pk_mul_f32 v[46:47], v[56:57], v[58:59] op_sel_hi:[1,0]
	v_pk_mul_f32 v[48:49], v[54:55], v[58:59] op_sel_hi:[1,0]
	s_nop 0
	v_cvt_pk_bf16_f32 v48, v48, v49
	v_cvt_pk_bf16_f32 v49, v46, v47
	global_store_dwordx2 v[2:3], v[48:49], off offset:-3584
	global_load_dwordx4 v[46:49], v16, s[16:17] offset:1024
	s_waitcnt vmcnt(0)
	v_pk_mul_f32 v[40:41], v[40:41], v[48:49]
	v_pk_mul_f32 v[38:39], v[38:39], v[46:47]
	v_pk_mul_f32 v[40:41], v[40:41], v[58:59] op_sel_hi:[1,0]
	v_pk_mul_f32 v[38:39], v[38:39], v[58:59] op_sel_hi:[1,0]
	s_nop 0
	v_cvt_pk_bf16_f32 v38, v38, v39
	v_cvt_pk_bf16_f32 v39, v40, v41
	global_store_dwordx2 v[2:3], v[38:39], off offset:-3072
	global_load_dwordx4 v[38:41], v16, s[16:17] offset:2048
	s_waitcnt vmcnt(0)
	v_pk_mul_f32 v[40:41], v[44:45], v[40:41]
	v_pk_mul_f32 v[38:39], v[42:43], v[38:39]
	v_pk_mul_f32 v[40:41], v[40:41], v[58:59] op_sel_hi:[1,0]
	v_pk_mul_f32 v[38:39], v[38:39], v[58:59] op_sel_hi:[1,0]
	s_nop 0
	v_cvt_pk_bf16_f32 v38, v38, v39
	v_cvt_pk_bf16_f32 v39, v40, v41
	global_store_dwordx2 v[2:3], v[38:39], off offset:-2560
	global_load_dwordx4 v[38:41], v16, s[16:17] offset:3072
	s_waitcnt vmcnt(0)
	v_pk_mul_f32 v[32:33], v[32:33], v[40:41]
	v_pk_mul_f32 v[30:31], v[30:31], v[38:39]
	v_pk_mul_f32 v[32:33], v[32:33], v[58:59] op_sel_hi:[1,0]
	v_pk_mul_f32 v[30:31], v[30:31], v[58:59] op_sel_hi:[1,0]
	s_nop 0
	v_cvt_pk_bf16_f32 v30, v30, v31
	v_cvt_pk_bf16_f32 v31, v32, v33
	global_store_dwordx2 v[2:3], v[30:31], off offset:-2048
	global_load_dwordx4 v[30:33], v17, s[16:17]
	s_waitcnt vmcnt(0)
	v_pk_mul_f32 v[24:25], v[24:25], v[32:33]
	v_pk_mul_f32 v[22:23], v[22:23], v[30:31]
	v_pk_mul_f32 v[24:25], v[24:25], v[58:59] op_sel_hi:[1,0]
	v_pk_mul_f32 v[22:23], v[22:23], v[58:59] op_sel_hi:[1,0]
	s_nop 0
	v_cvt_pk_bf16_f32 v22, v22, v23
	v_cvt_pk_bf16_f32 v23, v24, v25
	global_store_dwordx2 v[2:3], v[22:23], off offset:-1536
	global_load_dwordx4 v[22:25], v18, s[16:17]
	s_waitcnt vmcnt(0)
	v_pk_mul_f32 v[24:25], v[28:29], v[24:25]
	v_pk_mul_f32 v[22:23], v[26:27], v[22:23]
	v_pk_mul_f32 v[24:25], v[24:25], v[58:59] op_sel_hi:[1,0]
	v_pk_mul_f32 v[22:23], v[22:23], v[58:59] op_sel_hi:[1,0]
	s_nop 0
	v_cvt_pk_bf16_f32 v22, v22, v23
	v_cvt_pk_bf16_f32 v23, v24, v25
	global_store_dwordx2 v[2:3], v[22:23], off offset:-1024
	global_load_dwordx4 v[22:25], v19, s[16:17]
	s_waitcnt vmcnt(0)
	v_pk_mul_f32 v[24:25], v[36:37], v[24:25]
	v_pk_mul_f32 v[22:23], v[34:35], v[22:23]
	v_pk_mul_f32 v[24:25], v[58:59], v[24:25] op_sel_hi:[0,1]
	v_pk_mul_f32 v[22:23], v[58:59], v[22:23] op_sel_hi:[0,1]
	v_cvt_pk_bf16_f32 v22, v22, v23
	v_cvt_pk_bf16_f32 v23, v24, v25
	global_store_dwordx2 v[2:3], v[22:23], off offset:-512
	global_load_dwordx4 v[22:25], v20, s[16:17]
	s_waitcnt vmcnt(0)
	v_pk_mul_f32 v[24:25], v[52:53], v[24:25]
	v_pk_mul_f32 v[22:23], v[50:51], v[22:23]
	v_pk_mul_f32 v[24:25], v[58:59], v[24:25] op_sel_hi:[0,1]
	v_pk_mul_f32 v[22:23], v[58:59], v[22:23] op_sel_hi:[0,1]
	v_cvt_pk_bf16_f32 v22, v22, v23
	v_cvt_pk_bf16_f32 v23, v24, v25
	global_store_dwordx2 v[2:3], v[22:23], off
	v_lshl_add_u64 v[2:3], v[2:3], 0, s[12:13]
	s_cbranch_scc1 .LBB0_58

.LBB0_96:
	s_or_b64 exec, exec, s[8:9]
	s_lshl_b32 s8, s16, 5
	s_sub_i32 s8, s1, s8
	v_mov_b32_e32 v13, 0
	s_lshl_b32 s8, s8, 6
	v_ashrrev_i32_e32 v15, 4, v14
	v_cmp_lt_i32_e32 vcc, -1, v12
	s_waitcnt vmcnt(1)
	v_mov_b32_e32 v2, v13
	v_mov_b32_e32 v3, v13
	v_mov_b32_e32 v4, v13
	v_mov_b32_e32 v5, v13
	s_and_saveexec_b64 s[10:11], vcc
	s_cbranch_execz .LBB0_98
	v_add_u32_e32 v4, s8, v15
	s_mov_b32 s9, 0x139c0
	s_waitcnt lgkmcnt(0)
	v_mov_b64_e32 v[2:3], s[6:7]
	v_mad_i64_i32 v[2:3], s[12:13], v4, s9, v[2:3]
	v_lshl_add_u64 v[2:3], v[12:13], 2, v[2:3]
	global_load_dwordx4 v[2:5], v[2:3], off nt
.LBB0_98:
	s_or_b64 exec, exec, s[10:11]
	v_mov_b32_e32 v7, v13
	v_mov_b32_e32 v8, v13
	v_mov_b32_e32 v9, v13
	s_and_saveexec_b64 s[10:11], vcc
	s_cbranch_execz .LBB0_100
	v_add3_u32 v8, v15, s8, 32
	s_mov_b32 s9, 0x139c0
	s_waitcnt lgkmcnt(0)
	v_mov_b64_e32 v[6:7], s[6:7]
	v_mad_i64_i32 v[6:7], s[12:13], v8, s9, v[6:7]
	v_lshl_add_u64 v[6:7], v[12:13], 2, v[6:7]
	global_load_dwordx4 v[6:9], v[6:7], off nt
	s_waitcnt vmcnt(0)
	v_mov_b32_e32 v13, v6

.LBB0_134:
	s_or_b64 exec, exec, s[16:17]
	s_lshl_b32 s9, s9, 11
	s_sub_i32 s9, 0, s9
	v_cmp_lt_i32_e32 vcc, -1, v10
	v_mov_b32_e32 v2, v11
	v_mov_b32_e32 v3, v11
	v_mov_b32_e32 v4, v11
	v_mov_b32_e32 v5, v11
	s_and_saveexec_b64 s[16:17], vcc
	s_cbranch_execz .LBB0_136
	s_add_i32 s18, s9, s25
	v_add_u32_e32 v4, s18, v15
	v_mov_b64_e32 v[2:3], s[6:7]
	v_mad_i64_i32 v[2:3], s[18:19], v4, s33, v[2:3]
	v_lshl_add_u64 v[2:3], v[10:11], 2, v[2:3]
	global_load_dwordx4 v[2:5], v[2:3], off nt
.LBB0_136:
	s_or_b64 exec, exec, s[16:17]
	v_mov_b32_e32 v9, 0
	v_mov_b32_e32 v8, 0
	v_mov_b32_e32 v7, 0
	v_mov_b32_e32 v6, 0
	s_and_saveexec_b64 s[16:17], vcc
	s_cbranch_execz .LBB0_101
	s_add_i32 s18, s25, s9
	v_add3_u32 v8, s18, v15, 32
	v_mov_b64_e32 v[6:7], s[6:7]
	v_mad_i64_i32 v[6:7], s[18:19], v8, s33, v[6:7]
	v_lshl_add_u64 v[6:7], v[10:11], 2, v[6:7]
	global_load_dwordx4 v[6:9], v[6:7], off nt
	s_branch .LBB0_101

.LBB0_1076:
	v_lshl_add_u64 v[22:23], s[18:19], 0, v[0:1]
	v_add_co_u32_e32 v62, vcc, 0x10b00000, v22
	v_add_co_u32_e64 v46, s[4:5], s9, v22
	s_nop 0
	v_addc_co_u32_e32 v63, vcc, 0, v23, vcc
	v_addc_co_u32_e64 v47, s[4:5], 0, v23, s[4:5]
	global_load_dwordx4 v[34:37], v[46:47], off nt
	global_load_dwordx4 v[38:41], v[46:47], off offset:1024 nt
	global_load_dwordx4 v[42:45], v[46:47], off offset:2048 nt
	s_nop 0
	global_load_dwordx4 v[46:49], v[46:47], off offset:3072 nt
	s_nop 0
	global_load_dwordx4 v[50:53], v[62:63], off nt
	global_load_dwordx4 v[54:57], v[62:63], off offset:1024 nt
	global_load_dwordx4 v[58:61], v[62:63], off offset:2048 nt
	s_nop 0
	global_load_dwordx4 v[62:65], v[62:63], off offset:3072 nt
	v_lshl_add_u64 v[24:25], s[20:21], 0, v[0:1]
	v_add_co_u32_e64 v74, s[4:5], s44, v24
	v_lshl_add_u64 v[26:27], s[14:15], 0, v[0:1]
	s_nop 0
	v_addc_co_u32_e64 v75, s[4:5], 0, v25, s[4:5]
	v_add_co_u32_e64 v76, s[4:5], s44, v26
	s_mov_b64 s[38:39], s[76:77]
	s_nop 0
	v_addc_co_u32_e64 v77, s[4:5], 0, v27, s[4:5]
	s_load_dwordx2 s[4:5], s[38:39], 0x18
	global_load_dwordx4 v[66:69], v[24:25], off nt
	s_mov_b64 s[22:23], s[76:77]
	s_mov_b64 s[24:25], s[76:77]
	s_mov_b64 s[26:27], s[76:77]
	s_waitcnt lgkmcnt(0)
	global_load_dwordx4 v[70:73], v4, s[4:5]
	s_mov_b64 s[28:29], s[76:77]
	s_mov_b64 s[30:31], s[76:77]
	s_mov_b64 s[34:35], s[76:77]
	s_mov_b64 s[36:37], s[76:77]
	s_mov_b64 s[42:43], s[76:77]
	s_mov_b64 s[40:41], s[76:77]
	s_add_i32 s8, s8, s10
	s_add_u32 s14, s14, s16
	s_addc_u32 s15, s15, s17
	s_add_u32 s18, s18, s16
	s_addc_u32 s19, s19, s17
	s_add_u32 s20, s20, s16
	s_addc_u32 s21, s21, s17
	s_cmpk_lt_i32 s8, 0x4000
	s_waitcnt vmcnt(9)
	v_mov_b32_e32 v78, v35
	s_waitcnt vmcnt(5)
	v_mul_f32_e32 v92, v51, v51
	s_waitcnt vmcnt(4)
	v_mul_f32_e32 v93, v55, v55
	v_mov_b32_e32 v79, v39
	s_waitcnt vmcnt(3)
	v_mul_f32_e32 v94, v59, v59
	v_fmac_f32_e32 v92, v50, v50
	v_fmac_f32_e32 v93, v54, v54
	v_mov_b32_e32 v22, v34
	v_mov_b32_e32 v23, v38
	s_waitcnt vmcnt(2)
	v_mul_f32_e32 v95, v63, v63
	v_pk_mul_f32 v[78:79], v[78:79], v[78:79]
	v_fmac_f32_e32 v94, v58, v58
	v_fmac_f32_e32 v92, v52, v52
	v_fmac_f32_e32 v93, v56, v56
	v_mov_b32_e32 v80, v36
	v_mov_b32_e32 v81, v40
	v_fmac_f32_e32 v95, v62, v62
	v_pk_fma_f32 v[22:23], v[22:23], v[22:23], v[78:79]
	v_fmac_f32_e32 v94, v60, v60
	v_fmac_f32_e32 v92, v53, v53
	v_fmac_f32_e32 v93, v57, v57
	v_mov_b32_e32 v86, v43
	v_mov_b32_e32 v87, v47
	v_fmac_f32_e32 v95, v64, v64
	v_pk_fma_f32 v[22:23], v[80:81], v[80:81], v[22:23]
	v_fmac_f32_e32 v94, v61, v61
	v_add_f32_e32 v80, v92, v93
	v_mov_b32_e32 v82, v37
	v_mov_b32_e32 v83, v41
	v_mov_b32_e32 v84, v42
	v_mov_b32_e32 v85, v46
	v_pk_mul_f32 v[86:87], v[86:87], v[86:87]
	v_fmac_f32_e32 v95, v65, v65
	v_add_f32_e32 v80, v80, v94
	v_mov_b32_e32 v88, v44
	v_mov_b32_e32 v89, v48
	v_pk_fma_f32 v[78:79], v[84:85], v[84:85], v[86:87]
	v_pk_fma_f32 v[22:23], v[82:83], v[82:83], v[22:23]
	v_add_f32_e32 v80, v80, v95
	v_mov_b32_e32 v90, v45
	v_mov_b32_e32 v91, v49
	v_pk_fma_f32 v[78:79], v[88:89], v[88:89], v[78:79]
	v_add_f32_e32 v22, v80, v22
	v_pk_fma_f32 v[78:79], v[90:91], v[90:91], v[78:79]
	v_add_f32_e32 v22, v22, v23
	v_add_f32_e32 v22, v22, v78
	v_add_f32_e32 v22, v22, v79
	ds_bpermute_b32 v23, v9, v22
	s_waitcnt vmcnt(0)
	v_pk_mul_f32 v[52:53], v[52:53], v[72:73]
	v_pk_mul_f32 v[50:51], v[50:51], v[70:71]
	s_waitcnt lgkmcnt(0)
	v_add_f32_e32 v22, v22, v23
	ds_bpermute_b32 v23, v28, v22
	s_waitcnt lgkmcnt(0)
	v_add_f32_e32 v22, v22, v23
	ds_bpermute_b32 v23, v29, v22
	s_waitcnt lgkmcnt(0)
	v_add_f32_e32 v22, v22, v23
	ds_bpermute_b32 v23, v30, v22
	s_waitcnt lgkmcnt(0)
	v_add_f32_e32 v22, v22, v23
	ds_bpermute_b32 v23, v31, v22
	s_waitcnt lgkmcnt(0)
	v_add_f32_e32 v22, v22, v23
	ds_bpermute_b32 v23, v32, v22
	s_waitcnt lgkmcnt(0)
	v_add_f32_e32 v22, v22, v23
	v_fmamk_f32 v22, v22, 0x3a000000, v33
	v_mul_f32_e32 v23, 0x4b800000, v22
	v_cmp_gt_f32_e32 vcc, s11, v22
	s_nop 1
	v_cndmask_b32_e32 v22, v22, v23, vcc
	v_rsq_f32_e32 v22, v22
	s_nop 0
	v_mul_f32_e32 v23, 0x45800000, v22
	v_cndmask_b32_e32 v78, v22, v23, vcc
	v_pk_fma_f32 v[50:51], v[50:51], v[78:79], v[66:67] op_sel_hi:[1,0,1]
	v_pk_fma_f32 v[52:53], v[52:53], v[78:79], v[68:69] op_sel_hi:[1,0,1]
	global_store_dwordx4 v[26:27], v[50:53], off
	s_load_dwordx2 s[4:5], s[22:23], 0x18
	global_load_dwordx4 v[66:69], v[24:25], off offset:1024 nt
	v_mul_f32_e32 v79, v51, v51
	v_fmac_f32_e32 v79, v50, v50
	v_fmac_f32_e32 v79, v52, v52
	s_waitcnt lgkmcnt(0)
	global_load_dwordx4 v[70:73], v4, s[4:5] offset:1024
	v_fmac_f32_e32 v79, v53, v53
	s_waitcnt vmcnt(0)
	v_pk_mul_f32 v[22:23], v[56:57], v[72:73]
	v_pk_mul_f32 v[54:55], v[54:55], v[70:71]
	v_pk_fma_f32 v[56:57], v[22:23], v[78:79], v[68:69] op_sel_hi:[1,0,1]
	v_pk_fma_f32 v[54:55], v[54:55], v[78:79], v[66:67] op_sel_hi:[1,0,1]
	global_store_dwordx4 v[26:27], v[54:57], off offset:1024
	s_load_dwordx2 s[4:5], s[24:25], 0x18
	global_load_dwordx4 v[66:69], v[24:25], off offset:2048 nt
	v_mul_f32_e32 v80, v55, v55
	v_fmac_f32_e32 v80, v54, v54
	v_fmac_f32_e32 v80, v56, v56
	s_waitcnt lgkmcnt(0)
	global_load_dwordx4 v[70:73], v4, s[4:5] offset:2048
	v_fmac_f32_e32 v80, v57, v57
	s_waitcnt vmcnt(0)
	v_pk_mul_f32 v[22:23], v[60:61], v[72:73]
	v_pk_mul_f32 v[58:59], v[58:59], v[70:71]
	v_pk_fma_f32 v[60:61], v[22:23], v[78:79], v[68:69] op_sel_hi:[1,0,1]
	v_pk_fma_f32 v[58:59], v[58:59], v[78:79], v[66:67] op_sel_hi:[1,0,1]
	global_store_dwordx4 v[26:27], v[58:61], off offset:2048
	s_load_dwordx2 s[4:5], s[26:27], 0x18
	s_waitcnt lgkmcnt(0)
	global_load_dwordx4 v[66:69], v4, s[4:5] offset:3072
	s_nop 0
	global_load_dwordx4 v[22:25], v[24:25], off offset:3072 nt
	v_mul_f32_e32 v71, v59, v59
	v_fmac_f32_e32 v71, v58, v58
	v_fmac_f32_e32 v71, v60, v60
	v_add_f32_e32 v70, v79, v80
	v_fmac_f32_e32 v71, v61, v61
	v_add_f32_e32 v70, v71, v70
	s_waitcnt vmcnt(1)
	v_pk_mul_f32 v[64:65], v[64:65], v[68:69]
	v_pk_mul_f32 v[62:63], v[62:63], v[66:67]
	s_waitcnt vmcnt(0)
	v_pk_fma_f32 v[24:25], v[78:79], v[64:65], v[24:25] op_sel_hi:[0,1,1]
	v_pk_fma_f32 v[22:23], v[78:79], v[62:63], v[22:23] op_sel_hi:[0,1,1]
	global_store_dwordx4 v[26:27], v[22:25], off offset:3072
	s_load_dwordx2 s[4:5], s[28:29], 0x18
	s_waitcnt lgkmcnt(0)
	global_load_dwordx4 v[62:65], v6, s[4:5]
	global_load_dwordx4 v[66:69], v[74:75], off nt
	v_mul_f32_e32 v71, v23, v23
	v_fmac_f32_e32 v71, v22, v22
	v_fmac_f32_e32 v71, v24, v24
	v_fmac_f32_e32 v71, v25, v25
	s_waitcnt vmcnt(1)
	v_pk_mul_f32 v[26:27], v[36:37], v[64:65]
	v_pk_mul_f32 v[34:35], v[34:35], v[62:63]
	s_waitcnt vmcnt(0)
	v_pk_fma_f32 v[36:37], v[78:79], v[26:27], v[68:69] op_sel_hi:[0,1,1]
	v_pk_fma_f32 v[34:35], v[78:79], v[34:35], v[66:67] op_sel_hi:[0,1,1]
	global_store_dwordx4 v[76:77], v[34:37], off
	s_load_dwordx2 s[4:5], s[30:31], 0x18
	s_waitcnt lgkmcnt(0)
	global_load_dwordx4 v[62:65], v10, s[4:5]
	global_load_dwordx4 v[66:69], v[74:75], off offset:1024 nt
	v_mov_b32_e32 v80, v35
	v_mov_b32_e32 v72, v34
	s_waitcnt vmcnt(1)
	v_pk_mul_f32 v[26:27], v[40:41], v[64:65]
	v_pk_mul_f32 v[38:39], v[38:39], v[62:63]
	s_waitcnt vmcnt(0)
	v_pk_fma_f32 v[40:41], v[78:79], v[26:27], v[68:69] op_sel_hi:[0,1,1]
	v_pk_fma_f32 v[38:39], v[78:79], v[38:39], v[66:67] op_sel_hi:[0,1,1]
	global_store_dwordx4 v[76:77], v[38:41], off offset:1024
	s_load_dwordx2 s[4:5], s[34:35], 0x18
	s_waitcnt lgkmcnt(0)
	global_load_dwordx4 v[62:65], v12, s[4:5]
	global_load_dwordx4 v[66:69], v[74:75], off offset:2048 nt
	v_add_f32_e32 v79, v70, v71
	v_mov_b32_e32 v81, v39
	v_mov_b32_e32 v73, v38
	v_mov_b32_e32 v70, v36
	v_mov_b32_e32 v71, v40
	v_mov_b32_e32 v26, v37
	v_mov_b32_e32 v27, v41
	s_waitcnt vmcnt(1)
	v_pk_mul_f32 v[44:45], v[44:45], v[64:65]
	v_pk_mul_f32 v[42:43], v[42:43], v[62:63]
	s_waitcnt vmcnt(0)
	v_pk_fma_f32 v[44:45], v[78:79], v[44:45], v[68:69] op_sel_hi:[0,1,1]
	v_pk_fma_f32 v[42:43], v[78:79], v[42:43], v[66:67] op_sel_hi:[0,1,1]
	global_store_dwordx4 v[76:77], v[42:45], off offset:2048
	s_load_dwordx2 s[4:5], s[36:37], 0x18
	s_waitcnt lgkmcnt(0)
	global_load_dwordx4 v[62:65], v14, s[4:5]
	global_load_dwordx4 v[66:69], v[74:75], off offset:3072 nt
	v_pk_mul_f32 v[74:75], v[80:81], v[80:81]
	s_waitcnt vmcnt(1)
	v_pk_mul_f32 v[46:47], v[46:47], v[62:63]
	v_pk_fma_f32 v[72:73], v[72:73], v[72:73], v[74:75]
	v_pk_mul_f32 v[48:49], v[48:49], v[64:65]
	v_pk_fma_f32 v[70:71], v[70:71], v[70:71], v[72:73]
	v_mov_b32_e32 v74, v43
	v_pk_fma_f32 v[26:27], v[26:27], v[26:27], v[70:71]
	v_mov_b32_e32 v72, v42
	v_add_f32_e32 v26, v79, v26
	v_add_f32_e32 v79, v26, v27
	s_waitcnt vmcnt(0)
	v_pk_fma_f32 v[46:47], v[78:79], v[46:47], v[66:67] op_sel_hi:[0,1,1]
	v_pk_fma_f32 v[48:49], v[78:79], v[48:49], v[68:69] op_sel_hi:[0,1,1]
	v_mov_b32_e32 v75, v47
	global_store_dwordx4 v[76:77], v[46:49], off offset:3072
	v_mov_b32_e32 v73, v46
	v_pk_mul_f32 v[62:63], v[74:75], v[74:75]
	s_load_dwordx2 s[4:5], s[42:43], 0x10
	v_mov_b32_e32 v70, v44
	v_mov_b32_e32 v71, v48
	v_pk_fma_f32 v[62:63], v[72:73], v[72:73], v[62:63]
	v_mov_b32_e32 v26, v45
	v_mov_b32_e32 v27, v49
	v_pk_fma_f32 v[62:63], v[70:71], v[70:71], v[62:63]
	s_nop 0
	v_pk_fma_f32 v[26:27], v[26:27], v[26:27], v[62:63]
	s_nop 0
	v_add_f32_e32 v26, v79, v26
	v_add_f32_e32 v66, v26, v27
	s_waitcnt lgkmcnt(0)
	v_lshl_add_u64 v[26:27], s[4:5], 0, v[4:5]
	v_add_co_u32_e32 v26, vcc, s45, v26
	ds_bpermute_b32 v67, v9, v66
	s_nop 0
	v_addc_co_u32_e32 v27, vcc, 0, v27, vcc
	global_load_dwordx4 v[62:65], v[26:27], off nt
	s_waitcnt lgkmcnt(0)
	v_add_f32_e32 v26, v66, v67
	ds_bpermute_b32 v27, v28, v26
	s_waitcnt lgkmcnt(0)
	v_add_f32_e32 v26, v26, v27
	ds_bpermute_b32 v27, v29, v26
	s_waitcnt lgkmcnt(0)
	v_add_f32_e32 v26, v26, v27
	ds_bpermute_b32 v27, v30, v26
	s_waitcnt lgkmcnt(0)
	v_add_f32_e32 v26, v26, v27
	ds_bpermute_b32 v27, v31, v26
	s_waitcnt lgkmcnt(0)
	v_add_f32_e32 v26, v26, v27
	ds_bpermute_b32 v27, v32, v26
	s_waitcnt lgkmcnt(0)
	v_add_f32_e32 v26, v26, v27
	v_fmamk_f32 v26, v26, 0x3a000000, v33
	v_mul_f32_e32 v27, 0x4b800000, v26
	v_cmp_gt_f32_e32 vcc, s11, v26
	s_waitcnt vmcnt(0)
	v_pk_mul_f32 v[50:51], v[50:51], v[62:63]
	v_cndmask_b32_e32 v26, v26, v27, vcc
	v_rsq_f32_e32 v26, v26
	v_pk_mul_f32 v[52:53], v[52:53], v[64:65]
	v_mul_f32_e32 v27, 0x45800000, v26
	v_cndmask_b32_e32 v26, v26, v27, vcc
	v_pk_mul_f32 v[52:53], v[52:53], v[26:27] op_sel_hi:[1,0]
	v_pk_mul_f32 v[50:51], v[50:51], v[26:27] op_sel_hi:[1,0]
	s_nop 0
	v_cvt_pk_bf16_f32 v50, v50, v51
	v_cvt_pk_bf16_f32 v51, v52, v53
	global_store_dwordx2 v[2:3], v[50:51], off offset:-3584
	s_load_dwordx2 s[4:5], s[40:41], 0x10
	s_waitcnt lgkmcnt(0)
	v_lshl_add_u64 v[50:51], s[4:5], 0, v[16:17]
	v_add_co_u32_e32 v50, vcc, s45, v50
	s_mov_b64 s[4:5], s[76:77]
	s_nop 0
	v_addc_co_u32_e32 v51, vcc, 0, v51, vcc
	global_load_dwordx4 v[50:53], v[50:51], off nt
	s_waitcnt vmcnt(0)
	v_pk_mul_f32 v[50:51], v[54:55], v[50:51]
	v_pk_mul_f32 v[52:53], v[56:57], v[52:53]
	v_pk_mul_f32 v[50:51], v[50:51], v[26:27] op_sel_hi:[1,0]
	v_pk_mul_f32 v[52:53], v[52:53], v[26:27] op_sel_hi:[1,0]
	v_cvt_pk_bf16_f32 v50, v50, v51
	v_cvt_pk_bf16_f32 v51, v52, v53
	global_store_dwordx2 v[2:3], v[50:51], off offset:-3072
	s_load_dwordx2 s[4:5], s[4:5], 0x10
	s_waitcnt lgkmcnt(0)
	v_lshl_add_u64 v[50:51], s[4:5], 0, v[18:19]
	v_add_co_u32_e32 v50, vcc, s45, v50
	s_mov_b64 s[4:5], s[76:77]
	s_nop 0
	v_addc_co_u32_e32 v51, vcc, 0, v51, vcc
	global_load_dwordx4 v[50:53], v[50:51], off nt
	s_waitcnt vmcnt(0)
	v_pk_mul_f32 v[50:51], v[58:59], v[50:51]
	v_pk_mul_f32 v[52:53], v[60:61], v[52:53]
	v_pk_mul_f32 v[50:51], v[50:51], v[26:27] op_sel_hi:[1,0]
	v_pk_mul_f32 v[52:53], v[52:53], v[26:27] op_sel_hi:[1,0]
	v_cvt_pk_bf16_f32 v50, v50, v51
	v_cvt_pk_bf16_f32 v51, v52, v53
	global_store_dwordx2 v[2:3], v[50:51], off offset:-2560
	s_load_dwordx2 s[4:5], s[4:5], 0x10
	s_waitcnt lgkmcnt(0)
	v_lshl_add_u64 v[50:51], s[4:5], 0, v[20:21]
	v_add_co_u32_e32 v50, vcc, s45, v50
	s_mov_b64 s[4:5], s[76:77]
	s_nop 0
	v_addc_co_u32_e32 v51, vcc, 0, v51, vcc
	global_load_dwordx4 v[50:53], v[50:51], off nt
	s_waitcnt vmcnt(0)
	v_pk_mul_f32 v[22:23], v[22:23], v[50:51]
	v_pk_mul_f32 v[24:25], v[24:25], v[52:53]
	v_pk_mul_f32 v[22:23], v[26:27], v[22:23] op_sel_hi:[0,1]
	v_pk_mul_f32 v[24:25], v[26:27], v[24:25] op_sel_hi:[0,1]
	v_cvt_pk_bf16_f32 v22, v22, v23
	v_cvt_pk_bf16_f32 v23, v24, v25
	global_store_dwordx2 v[2:3], v[22:23], off offset:-2048
	s_load_dwordx2 s[4:5], s[4:5], 0x10
	s_waitcnt lgkmcnt(0)
	v_lshl_add_u64 v[22:23], s[4:5], 0, v[6:7]
	v_add_co_u32_e32 v22, vcc, s45, v22
	s_mov_b64 s[4:5], s[76:77]
	s_nop 0
	v_addc_co_u32_e32 v23, vcc, 0, v23, vcc
	global_load_dwordx4 v[22:25], v[22:23], off nt
	s_waitcnt vmcnt(0)
	v_pk_mul_f32 v[22:23], v[34:35], v[22:23]
	v_pk_mul_f32 v[24:25], v[36:37], v[24:25]
	v_pk_mul_f32 v[22:23], v[26:27], v[22:23] op_sel_hi:[0,1]
	v_pk_mul_f32 v[24:25], v[26:27], v[24:25] op_sel_hi:[0,1]
	v_cvt_pk_bf16_f32 v22, v22, v23
	v_cvt_pk_bf16_f32 v23, v24, v25
	global_store_dwordx2 v[2:3], v[22:23], off offset:-1536
	s_load_dwordx2 s[4:5], s[4:5], 0x10
	s_waitcnt lgkmcnt(0)
	v_lshl_add_u64 v[22:23], s[4:5], 0, v[10:11]
	v_add_co_u32_e32 v22, vcc, s45, v22
	s_mov_b64 s[4:5], s[76:77]
	s_nop 0
	v_addc_co_u32_e32 v23, vcc, 0, v23, vcc
	global_load_dwordx4 v[22:25], v[22:23], off nt
	s_waitcnt vmcnt(0)
	v_pk_mul_f32 v[22:23], v[38:39], v[22:23]
	v_pk_mul_f32 v[24:25], v[40:41], v[24:25]
	v_pk_mul_f32 v[22:23], v[26:27], v[22:23] op_sel_hi:[0,1]
	v_pk_mul_f32 v[24:25], v[26:27], v[24:25] op_sel_hi:[0,1]
	v_cvt_pk_bf16_f32 v22, v22, v23
	v_cvt_pk_bf16_f32 v23, v24, v25
	global_store_dwordx2 v[2:3], v[22:23], off offset:-1024
	s_load_dwordx2 s[4:5], s[4:5], 0x10
	s_waitcnt lgkmcnt(0)
	v_lshl_add_u64 v[22:23], s[4:5], 0, v[12:13]
	v_add_co_u32_e32 v22, vcc, s45, v22
	s_mov_b64 s[4:5], s[76:77]
	s_nop 0
	v_addc_co_u32_e32 v23, vcc, 0, v23, vcc
	global_load_dwordx4 v[22:25], v[22:23], off nt
	s_waitcnt vmcnt(0)
	v_pk_mul_f32 v[22:23], v[42:43], v[22:23]
	v_pk_mul_f32 v[24:25], v[44:45], v[24:25]
	v_pk_mul_f32 v[22:23], v[26:27], v[22:23] op_sel_hi:[0,1]
	v_pk_mul_f32 v[24:25], v[26:27], v[24:25] op_sel_hi:[0,1]
	v_cvt_pk_bf16_f32 v22, v22, v23
	v_cvt_pk_bf16_f32 v23, v24, v25
	global_store_dwordx2 v[2:3], v[22:23], off offset:-512
	s_load_dwordx2 s[4:5], s[4:5], 0x10
	s_waitcnt lgkmcnt(0)
	v_lshl_add_u64 v[22:23], s[4:5], 0, v[14:15]
	v_add_co_u32_e32 v22, vcc, s45, v22
	s_nop 1
	v_addc_co_u32_e32 v23, vcc, 0, v23, vcc
	global_load_dwordx4 v[22:25], v[22:23], off nt
	s_waitcnt vmcnt(0)
	v_pk_mul_f32 v[22:23], v[46:47], v[22:23]
	v_pk_mul_f32 v[24:25], v[48:49], v[24:25]
	v_pk_mul_f32 v[22:23], v[26:27], v[22:23] op_sel_hi:[0,1]
	v_pk_mul_f32 v[24:25], v[26:27], v[24:25] op_sel_hi:[0,1]
	v_cvt_pk_bf16_f32 v22, v22, v23
	v_cvt_pk_bf16_f32 v23, v24, v25
	global_store_dwordx2 v[2:3], v[22:23], off
	v_lshl_add_u64 v[2:3], v[2:3], 0, s[12:13]
	s_cbranch_scc1 .LBB0_1076

.LBB0_1113:
	s_or_b64 exec, exec, s[8:9]
	s_lshl_b32 s8, s16, 5
	s_sub_i32 s8, s33, s8
	s_lshl_b32 s8, s8, 6
	s_waitcnt lgkmcnt(0)
	s_add_u32 s4, s4, 0x9ce0000
	v_mov_b32_e32 v11, 0
	v_ashrrev_i32_e32 v13, 4, v8
	s_addc_u32 s5, s5, 0
	v_cmp_lt_i32_e32 vcc, -1, v10
	v_mov_b32_e32 v0, v11
	v_mov_b32_e32 v1, v11
	v_mov_b32_e32 v2, v11
	v_mov_b32_e32 v3, v11
	s_and_saveexec_b64 s[10:11], vcc
	s_cbranch_execz .LBB0_1115
	v_add_u32_e32 v2, s8, v13
	s_mov_b32 s9, 0x139c0
	v_mov_b64_e32 v[0:1], s[4:5]
	v_mad_i64_i32 v[0:1], s[12:13], v2, s9, v[0:1]
	v_lshl_add_u64 v[0:1], v[10:11], 2, v[0:1]
	global_load_dwordx4 v[0:3], v[0:1], off nt
.LBB0_1115:
	s_or_b64 exec, exec, s[10:11]
	v_mov_b32_e32 v5, v11
	v_mov_b32_e32 v6, v11
	v_mov_b32_e32 v7, v11
	s_and_saveexec_b64 s[10:11], vcc
	s_cbranch_execz .LBB0_1117
	v_add3_u32 v6, v13, s8, 32
	s_mov_b32 s9, 0x139c0
	v_mov_b64_e32 v[4:5], s[4:5]
	v_mad_i64_i32 v[4:5], s[12:13], v6, s9, v[4:5]
	v_lshl_add_u64 v[4:5], v[10:11], 2, v[4:5]
	global_load_dwordx4 v[4:7], v[4:5], off nt
	s_waitcnt vmcnt(0)
	v_mov_b32_e32 v11, v4

.LBB0_1151:
	s_or_b64 exec, exec, s[16:17]
	s_lshl_b32 s9, s9, 11
	s_sub_i32 s9, 0, s9
	v_cmp_lt_i32_e32 vcc, -1, v8
	v_mov_b32_e32 v0, v9
	v_mov_b32_e32 v1, v9
	v_mov_b32_e32 v2, v9
	v_mov_b32_e32 v3, v9
	s_and_saveexec_b64 s[16:17], vcc
	s_cbranch_execz .LBB0_1153
	s_add_i32 s18, s9, s25
	v_add_u32_e32 v2, s18, v13
	v_mov_b64_e32 v[0:1], s[4:5]
	v_mad_i64_i32 v[0:1], s[18:19], v2, s34, v[0:1]
	v_lshl_add_u64 v[0:1], v[8:9], 2, v[0:1]
	global_load_dwordx4 v[0:3], v[0:1], off nt
.LBB0_1153:
	s_or_b64 exec, exec, s[16:17]
	v_mov_b32_e32 v7, 0
	v_mov_b32_e32 v6, 0
	v_mov_b32_e32 v5, 0
	v_mov_b32_e32 v4, 0
	s_and_saveexec_b64 s[16:17], vcc
	s_cbranch_execz .LBB0_1118
	s_add_i32 s18, s25, s9
	v_add3_u32 v6, s18, v13, 32
	v_mov_b64_e32 v[4:5], s[4:5]
	v_mad_i64_i32 v[4:5], s[18:19], v6, s34, v[4:5]
	v_lshl_add_u64 v[4:5], v[8:9], 2, v[4:5]
	global_load_dwordx4 v[4:7], v[4:5], off nt
	s_branch .LBB0_1118

.LBB0_2130:
	v_lshl_add_u64 v[42:43], s[10:11], 0, v[8:9]
	v_add_co_u32_e32 v58, vcc, 0x10b00000, v42
	v_add_co_u32_e64 v44, s[2:3], s0, v42
	s_nop 0
	v_addc_co_u32_e32 v59, vcc, 0, v43, vcc
	v_addc_co_u32_e64 v45, s[2:3], 0, v43, s[2:3]
	s_mov_b64 s[18:19], s[76:77]
	global_load_dwordx4 v[34:37], v[44:45], off nt
	global_load_dwordx4 v[38:41], v[44:45], off offset:1024 nt
	global_load_dwordx4 v[4:7], v[44:45], off offset:2048 nt
	global_load_dwordx4 v[0:3], v[44:45], off offset:3072 nt
	s_nop 0
	global_load_dwordx4 v[42:45], v[58:59], off nt
	global_load_dwordx4 v[46:49], v[58:59], off offset:1024 nt
	global_load_dwordx4 v[50:53], v[58:59], off offset:2048 nt
	global_load_dwordx4 v[54:57], v[58:59], off offset:3072 nt
	s_load_dwordx2 s[2:3], s[18:19], 0x18
	v_lshl_add_u64 v[66:67], s[14:15], 0, v[8:9]
	global_load_dwordx4 v[58:61], v[66:67], off nt
	s_mov_b64 s[20:21], s[76:77]
	s_add_i32 s6, s6, s8
	s_waitcnt lgkmcnt(0)
	v_lshl_add_u64 v[62:63], s[2:3], 0, v[10:11]
	v_add_co_u32_e32 v62, vcc, s7, v62
	s_add_u32 s10, s10, s12
	s_nop 0
	v_addc_co_u32_e32 v63, vcc, 0, v63, vcc
	global_load_dwordx4 v[62:65], v[62:63], off nt
	s_addc_u32 s11, s11, s13
	s_add_u32 s14, s14, s12
	s_addc_u32 s15, s15, s13
	s_cmpk_lt_i32 s6, 0x4000
	s_waitcnt vmcnt(9)
	v_mov_b32_e32 v70, v35
	s_waitcnt vmcnt(5)
	v_mul_f32_e32 v33, v43, v43
	s_waitcnt vmcnt(4)
	v_mul_f32_e32 v84, v47, v47
	s_waitcnt vmcnt(3)
	v_mul_f32_e32 v85, v51, v51
	v_fmac_f32_e32 v33, v42, v42
	v_fmac_f32_e32 v84, v46, v46
	v_mov_b32_e32 v71, v39
	s_waitcnt vmcnt(2)
	v_mul_f32_e32 v86, v55, v55
	v_fmac_f32_e32 v85, v50, v50
	v_fmac_f32_e32 v33, v44, v44
	v_fmac_f32_e32 v84, v48, v48
	v_mov_b32_e32 v68, v34
	v_mov_b32_e32 v69, v38
	v_pk_mul_f32 v[70:71], v[70:71], v[70:71]
	v_fmac_f32_e32 v86, v54, v54
	v_fmac_f32_e32 v85, v52, v52
	v_fmac_f32_e32 v33, v45, v45
	v_fmac_f32_e32 v84, v49, v49
	v_mov_b32_e32 v72, v36
	v_mov_b32_e32 v73, v40
	v_mov_b32_e32 v78, v5
	v_mov_b32_e32 v79, v1
	v_pk_fma_f32 v[68:69], v[68:69], v[68:69], v[70:71]
	v_fmac_f32_e32 v86, v56, v56
	v_fmac_f32_e32 v85, v53, v53
	v_add_f32_e32 v33, v33, v84
	v_mov_b32_e32 v74, v37
	v_mov_b32_e32 v75, v41
	v_mov_b32_e32 v76, v4
	v_mov_b32_e32 v77, v0
	v_pk_mul_f32 v[78:79], v[78:79], v[78:79]
	v_pk_fma_f32 v[68:69], v[72:73], v[72:73], v[68:69]
	v_fmac_f32_e32 v86, v57, v57
	v_add_f32_e32 v33, v33, v85
	v_mov_b32_e32 v80, v6
	v_mov_b32_e32 v81, v2
	v_pk_fma_f32 v[70:71], v[76:77], v[76:77], v[78:79]
	v_pk_fma_f32 v[68:69], v[74:75], v[74:75], v[68:69]
	v_add_f32_e32 v33, v33, v86
	v_mov_b32_e32 v82, v7
	v_mov_b32_e32 v83, v3
	v_pk_fma_f32 v[70:71], v[80:81], v[80:81], v[70:71]
	v_add_f32_e32 v33, v33, v68
	v_pk_fma_f32 v[70:71], v[82:83], v[82:83], v[70:71]
	v_add_f32_e32 v33, v33, v69
	v_add_f32_e32 v33, v33, v70
	v_add_f32_e32 v33, v33, v71
	s_waitcnt vmcnt(0)
	v_pk_mul_f32 v[42:43], v[42:43], v[62:63]
	ds_bpermute_b32 v62, v26, v33
	v_pk_mul_f32 v[44:45], v[44:45], v[64:65]
	s_waitcnt lgkmcnt(0)
	v_add_f32_e32 v33, v33, v62
	ds_bpermute_b32 v62, v27, v33
	s_waitcnt lgkmcnt(0)
	v_add_f32_e32 v33, v33, v62
	ds_bpermute_b32 v62, v28, v33
	s_waitcnt lgkmcnt(0)
	v_add_f32_e32 v33, v33, v62
	ds_bpermute_b32 v62, v29, v33
	s_waitcnt lgkmcnt(0)
	v_add_f32_e32 v33, v33, v62
	ds_bpermute_b32 v62, v30, v33
	s_waitcnt lgkmcnt(0)
	v_add_f32_e32 v33, v33, v62
	ds_bpermute_b32 v62, v31, v33
	s_waitcnt lgkmcnt(0)
	v_add_f32_e32 v33, v33, v62
	v_fmamk_f32 v33, v33, 0x3a000000, v32
	v_mul_f32_e32 v62, 0x4b800000, v33
	v_cmp_gt_f32_e32 vcc, s1, v33
	s_nop 1
	v_cndmask_b32_e32 v33, v33, v62, vcc
	v_rsq_f32_e32 v33, v33
	s_nop 0
	v_mul_f32_e32 v62, 0x45800000, v33
	v_cndmask_b32_e32 v62, v33, v62, vcc
	v_pk_fma_f32 v[44:45], v[44:45], v[62:63], v[60:61] op_sel_hi:[1,0,1]
	v_pk_fma_f32 v[42:43], v[42:43], v[62:63], v[58:59] op_sel_hi:[1,0,1]
	global_store_dwordx4 v[66:67], v[42:45], off
	s_load_dwordx2 s[2:3], s[20:21], 0x18
	s_waitcnt lgkmcnt(0)
	v_lshl_add_u64 v[42:43], s[2:3], 0, v[12:13]
	v_add_co_u32_e32 v64, vcc, s7, v42
	s_mov_b64 s[2:3], s[76:77]
	s_nop 0
	v_addc_co_u32_e32 v65, vcc, 0, v43, vcc
	global_load_dwordx4 v[42:45], v[64:65], off nt
	global_load_dwordx4 v[58:61], v[66:67], off offset:1024 nt
	s_waitcnt vmcnt(1)
	v_pk_mul_f32 v[44:45], v[48:49], v[44:45]
	v_pk_mul_f32 v[42:43], v[46:47], v[42:43]
	s_waitcnt vmcnt(0)
	v_pk_fma_f32 v[44:45], v[44:45], v[62:63], v[60:61] op_sel_hi:[1,0,1]
	v_pk_fma_f32 v[42:43], v[42:43], v[62:63], v[58:59] op_sel_hi:[1,0,1]
	global_store_dwordx4 v[66:67], v[42:45], off offset:1024
	s_load_dwordx2 s[2:3], s[2:3], 0x18
	s_waitcnt lgkmcnt(0)
	v_lshl_add_u64 v[42:43], s[2:3], 0, v[14:15]
	v_add_co_u32_e32 v58, vcc, s7, v42
	s_mov_b64 s[2:3], s[76:77]
	s_nop 0
	v_addc_co_u32_e32 v59, vcc, 0, v43, vcc
	global_load_dwordx4 v[42:45], v[58:59], off nt
	global_load_dwordx4 v[46:49], v[66:67], off offset:2048 nt
	s_waitcnt vmcnt(1)
	v_pk_mul_f32 v[44:45], v[52:53], v[44:45]
	v_pk_mul_f32 v[42:43], v[50:51], v[42:43]
	s_waitcnt vmcnt(0)
	v_pk_fma_f32 v[44:45], v[44:45], v[62:63], v[48:49] op_sel_hi:[1,0,1]
	v_pk_fma_f32 v[42:43], v[42:43], v[62:63], v[46:47] op_sel_hi:[1,0,1]
	global_store_dwordx4 v[66:67], v[42:45], off offset:2048
	s_load_dwordx2 s[2:3], s[2:3], 0x18
	s_waitcnt lgkmcnt(0)
	v_lshl_add_u64 v[42:43], s[2:3], 0, v[16:17]
	v_add_co_u32_e32 v50, vcc, s7, v42
	s_mov_b64 s[2:3], s[76:77]
	s_nop 0
	v_addc_co_u32_e32 v51, vcc, 0, v43, vcc
	global_load_dwordx4 v[42:45], v[50:51], off nt
	global_load_dwordx4 v[46:49], v[66:67], off offset:3072 nt
	v_add_co_u32_e32 v50, vcc, s9, v66
	s_waitcnt vmcnt(1)
	v_pk_mul_f32 v[44:45], v[56:57], v[44:45]
	v_pk_mul_f32 v[42:43], v[54:55], v[42:43]
	s_waitcnt vmcnt(0)
	v_pk_fma_f32 v[44:45], v[62:63], v[44:45], v[48:49] op_sel_hi:[0,1,1]
	v_pk_fma_f32 v[42:43], v[62:63], v[42:43], v[46:47] op_sel_hi:[0,1,1]
	global_store_dwordx4 v[66:67], v[42:45], off offset:3072
	s_load_dwordx2 s[2:3], s[2:3], 0x18
	v_addc_co_u32_e32 v51, vcc, 0, v67, vcc
	s_waitcnt lgkmcnt(0)
	v_lshl_add_u64 v[42:43], s[2:3], 0, v[18:19]
	v_add_co_u32_e32 v52, vcc, s7, v42
	s_mov_b64 s[2:3], s[76:77]
	s_nop 0
	v_addc_co_u32_e32 v53, vcc, 0, v43, vcc
	global_load_dwordx4 v[42:45], v[52:53], off nt
	global_load_dwordx4 v[46:49], v[50:51], off nt
	s_waitcnt vmcnt(1)
	v_pk_mul_f32 v[36:37], v[36:37], v[44:45]
	v_pk_mul_f32 v[34:35], v[34:35], v[42:43]
	s_waitcnt vmcnt(0)
	v_pk_fma_f32 v[36:37], v[62:63], v[36:37], v[48:49] op_sel_hi:[0,1,1]
	v_pk_fma_f32 v[34:35], v[62:63], v[34:35], v[46:47] op_sel_hi:[0,1,1]
	global_store_dwordx4 v[50:51], v[34:37], off
	s_load_dwordx2 s[2:3], s[2:3], 0x18
	s_waitcnt lgkmcnt(0)
	v_lshl_add_u64 v[34:35], s[2:3], 0, v[20:21]
	v_add_co_u32_e32 v46, vcc, s7, v34
	s_mov_b64 s[2:3], s[76:77]
	s_nop 0
	v_addc_co_u32_e32 v47, vcc, 0, v35, vcc
	global_load_dwordx4 v[34:37], v[46:47], off nt
	global_load_dwordx4 v[42:45], v[50:51], off offset:1024 nt
	s_waitcnt vmcnt(1)
	v_pk_mul_f32 v[36:37], v[40:41], v[36:37]
	v_pk_mul_f32 v[34:35], v[38:39], v[34:35]
	s_waitcnt vmcnt(0)
	v_pk_fma_f32 v[36:37], v[62:63], v[36:37], v[44:45] op_sel_hi:[0,1,1]
	v_pk_fma_f32 v[34:35], v[62:63], v[34:35], v[42:43] op_sel_hi:[0,1,1]
	global_store_dwordx4 v[50:51], v[34:37], off offset:1024
	s_load_dwordx2 s[2:3], s[2:3], 0x18
	s_waitcnt lgkmcnt(0)
	v_lshl_add_u64 v[34:35], s[2:3], 0, v[22:23]
	v_add_co_u32_e32 v42, vcc, s7, v34
	s_mov_b64 s[2:3], s[76:77]
	s_nop 0
	v_addc_co_u32_e32 v43, vcc, 0, v35, vcc
	global_load_dwordx4 v[34:37], v[42:43], off nt
	global_load_dwordx4 v[38:41], v[50:51], off offset:2048 nt
	s_waitcnt vmcnt(1)
	v_pk_mul_f32 v[6:7], v[6:7], v[36:37]
	v_pk_mul_f32 v[4:5], v[4:5], v[34:35]
	s_waitcnt vmcnt(0)
	v_pk_fma_f32 v[6:7], v[62:63], v[6:7], v[40:41] op_sel_hi:[0,1,1]
	v_pk_fma_f32 v[4:5], v[62:63], v[4:5], v[38:39] op_sel_hi:[0,1,1]
	global_store_dwordx4 v[50:51], v[4:7], off offset:2048
	s_load_dwordx2 s[2:3], s[2:3], 0x18
	s_waitcnt lgkmcnt(0)
	v_lshl_add_u64 v[4:5], s[2:3], 0, v[24:25]
	v_add_co_u32_e32 v38, vcc, s7, v4
	s_nop 1
	v_addc_co_u32_e32 v39, vcc, 0, v5, vcc
	global_load_dwordx4 v[4:7], v[38:39], off nt
	global_load_dwordx4 v[34:37], v[50:51], off offset:3072 nt
	s_waitcnt vmcnt(1)
	v_pk_mul_f32 v[2:3], v[2:3], v[6:7]
	v_pk_mul_f32 v[0:1], v[0:1], v[4:5]
	s_waitcnt vmcnt(0)
	v_pk_fma_f32 v[2:3], v[62:63], v[2:3], v[36:37] op_sel_hi:[0,1,1]
	v_pk_fma_f32 v[0:1], v[62:63], v[0:1], v[34:35] op_sel_hi:[0,1,1]
	global_store_dwordx4 v[50:51], v[0:3], off offset:3072
	s_cbranch_scc1 .LBB0_2130
